# code placement: s_nop pads so that every hot loop head (BATT, FoX, both GEMM K-loops) sits at the baseline's offset mod 8
# baseline (speedup 1.0000x reference)
.LBB0_83:
	s_mov_b32 s100, 1
	s_or_b64 exec, exec, s[28:29]
	s_and_b64 vcc, exec, s[70:71]
	s_mov_b32 s66, s54
	s_mov_b32 s67, s47
	s_mov_b32 s84, s52
	s_mov_b64 s[42:43], s[72:73]
	s_mov_b64 s[50:51], s[6:7]
	s_mov_b32 s89, s34
	s_waitcnt lgkmcnt(0)
	s_barrier
	s_cbranch_vccnz .LBB0_134
	s_nop 0

.LBB0_99:
	v_mov_b32_e32 v142, 0
	v_mov_b32_e32 v143, v142
	v_mov_b32_e32 v144, v142
	v_mov_b32_e32 v145, v142
	s_nop 0

.Lmy_fox_nopub:
	s_cmp_lg_u32 s101, 0
	s_addc_u32 s29, s9, 0
	v_max3_f32 v32, v32, v8, v9
	v_max3_f32 v33, v33, v10, v11
	s_mov_b32 s1, m0
	s_mov_b32 m0, s89
	s_nop 0
	global_load_lds_dwordx4 v190, s[28:29]
	s_mov_b32 m0, s1
	s_add_u32 s28, s10, 0x20000
	v_max3_f32 v32, v32, v24, v25
	v_max3_f32 v33, v33, v26, v27
	s_addc_u32 s29, s11, 0
	v_max3_f32 v32, v32, v12, v13
	v_max3_f32 v33, v33, v14, v15
	s_cmp_lg_u32 0, -1
	v_max3_f32 v32, v32, v28, v29
	v_max3_f32 v33, v33, v30, v31
	s_cselect_b32 s1, 0, 0
	v_max_f32_e32 v32, v32, v33
	s_add_i32 s1, s1, s31
	v_mov_b32_e32 v33, v32
	s_nop 1
	v_permlane32_swap_b32_e32 v32, v33
	v_max_f32_e32 v32, v32, v33
	s_add_i32 s1, s1, 0x8000
	s_mov_b32 s31, m0
	s_mov_b32 m0, s1
	s_nop 0
	global_load_lds_dwordx4 v191, s[28:29]
	s_mov_b32 m0, s31
	v_xor_b32_e32 v33, 0x80000000, v34
	v_add_f32_e32 v32, v33, v32
	ds_read_b128 v[162:165], v192 offset:8192
	ds_read_b128 v[158:161], v192 offset:8704
	ds_read_b128 v[154:157], v192 offset:10240
	ds_read_b128 v[150:153], v192 offset:10752
	ds_read_b128 v[146:149], v192 offset:12288
	ds_read_b128 v[142:145], v192 offset:12800
	ds_read_b128 v[138:141], v192 offset:14336
	ds_read_b128 v[134:137], v192 offset:14848
	v_xor_b32_e32 v32, 0x80000000, v32
	v_cvt_pk_bf16_f32 v34, v32, 0
	v_lshlrev_b32_e32 v34, 16, v34
	v_sub_f32_e32 v35, v32, v34
	s_waitcnt vmcnt(2) lgkmcnt(0)
	s_barrier
	s_mov_b32 s30, 1
	v_cvt_pk_bf16_f32 v194, v32, v35
	v_and_b32_e32 v32, 0xffff0000, v194
	v_add_f32_e32 v32, v34, v32
	s_mov_b32 s55, 0
	v_xor_b32_e32 v188, 0x80000000, v32
	v_sub_f32_e32 v32, v188, v33
	s_cmp_lt_i32 s78, 7
	v_sub_f32_e32 v0, v0, v32
	v_sub_f32_e32 v16, v16, v32
	v_sub_f32_e32 v1, v1, v32
	v_sub_f32_e32 v17, v17, v32
	v_sub_f32_e32 v2, v2, v32
	v_sub_f32_e32 v18, v18, v32
	v_sub_f32_e32 v3, v3, v32
	v_sub_f32_e32 v19, v19, v32
	v_sub_f32_e32 v4, v4, v32
	v_sub_f32_e32 v20, v20, v32
	v_sub_f32_e32 v5, v5, v32
	v_sub_f32_e32 v21, v21, v32
	v_sub_f32_e32 v6, v6, v32
	v_sub_f32_e32 v22, v22, v32
	v_sub_f32_e32 v7, v7, v32
	v_sub_f32_e32 v23, v23, v32
	v_sub_f32_e32 v8, v8, v32
	v_sub_f32_e32 v24, v24, v32
	v_sub_f32_e32 v9, v9, v32
	v_sub_f32_e32 v25, v25, v32
	v_sub_f32_e32 v10, v10, v32
	v_sub_f32_e32 v26, v26, v32
	v_sub_f32_e32 v11, v11, v32
	v_sub_f32_e32 v27, v27, v32
	v_sub_f32_e32 v12, v12, v32
	v_sub_f32_e32 v28, v28, v32
	v_sub_f32_e32 v13, v13, v32
	v_sub_f32_e32 v29, v29, v32
	v_sub_f32_e32 v14, v14, v32
	v_sub_f32_e32 v30, v30, v32
	v_sub_f32_e32 v15, v15, v32
	v_sub_f32_e32 v31, v31, v32
	s_nop 0
	v_exp_f32_e32 v48, v0
	v_exp_f32_e32 v49, v1
	v_exp_f32_e32 v50, v2
	v_exp_f32_e32 v51, v3
	v_exp_f32_e32 v52, v4
	v_exp_f32_e32 v53, v5
	v_exp_f32_e32 v54, v6
	v_exp_f32_e32 v55, v7
	v_exp_f32_e32 v56, v8
	v_exp_f32_e32 v57, v9
	v_exp_f32_e32 v58, v10
	v_exp_f32_e32 v59, v11
	v_exp_f32_e32 v60, v12
	v_exp_f32_e32 v61, v13
	v_exp_f32_e32 v62, v14
	v_exp_f32_e32 v63, v15
	v_exp_f32_e32 v32, v16
	v_exp_f32_e32 v33, v17
	v_exp_f32_e32 v34, v18
	v_exp_f32_e32 v35, v19
	v_exp_f32_e32 v36, v20
	v_exp_f32_e32 v37, v21
	v_exp_f32_e32 v38, v22
	v_exp_f32_e32 v39, v23
	v_exp_f32_e32 v40, v24
	v_exp_f32_e32 v41, v25
	v_exp_f32_e32 v42, v26
	v_exp_f32_e32 v43, v27
	v_exp_f32_e32 v44, v28
	v_exp_f32_e32 v45, v29
	v_exp_f32_e32 v46, v30
	v_exp_f32_e32 v47, v31
	s_cbranch_scc1 .LBB0_302
	s_add_u32 s10, s10, 0x60000
	s_addc_u32 s11, s11, 0
	v_mov_b32_e32 v14, v101
	v_mov_b32_e32 v15, v101
	s_add_u32 s30, s8, 0xa0000
	v_readlane_b32 s1, v243, 50
	v_mov_b32_e32 v0, v101
	v_mov_b32_e32 v1, v101
	v_mov_b32_e32 v2, v101
	v_mov_b32_e32 v3, v101
	v_mov_b32_e32 v4, v101
	v_mov_b32_e32 v5, v101
	v_mov_b32_e32 v6, v101
	v_mov_b32_e32 v7, v101
	v_mov_b32_e32 v8, v101
	v_mov_b32_e32 v9, v101
	v_mov_b32_e32 v10, v101
	v_mov_b32_e32 v11, v101
	v_mov_b32_e32 v12, v101
	v_mov_b32_e32 v13, v101
	v_mov_b64_e32 v[30:31], v[14:15]
	v_add_u32_e32 v65, s41, v170
	s_addc_u32 s31, s9, 0
	v_add_u32_e32 v171, s1, v170
	s_mov_b32 s60, 0
	s_movk_i32 s55, 0x4000
	s_movk_i32 s85, 0x2000
	v_mov_b32_e32 v64, 0
	s_mov_b32 s51, 6
	v_mov_b64_e32 v[28:29], v[12:13]
	v_mov_b64_e32 v[26:27], v[10:11]
	v_mov_b64_e32 v[24:25], v[8:9]
	v_mov_b64_e32 v[22:23], v[6:7]
	v_mov_b64_e32 v[20:21], v[4:5]
	v_mov_b64_e32 v[18:19], v[2:3]
	v_mov_b64_e32 v[16:17], v[0:1]
	s_nop 0

.LBB0_316:
	s_lshl_b32 s1, s30, 6
	s_add_i32 s1, s84, s1
	s_addk_i32 s1, 0x17b
	v_add_u32_e32 v66, s1, v184
	s_lshl_b32 s1, s30, 8
	s_add_i32 s1, s1, 0
	s_mov_b32 s31, s38
	v_subrev_u32_e32 v195, s52, v66
	s_sub_i32 s47, s50, s47
	s_add_i32 s52, s30, 2
	s_add_i32 s1, s1, 0x14800
	s_lshl_b64 s[30:31], s[30:31], 17
	s_add_u32 s50, s28, s30
	s_addc_u32 s51, s29, s31
	v_add_u32_e32 v196, s1, v170
	s_add_u32 s1, s8, s30
	s_addc_u32 s8, s9, s31
	s_add_u32 s84, s1, 0x80000
	v_add_u32_e32 v65, s41, v170
	s_addc_u32 s85, s8, 0
	s_nop 0
